# ret_r1: KT/VT transposed LDS images XOR-swizzled by row group (fewer bank conflicts on 16-bit stores)
# baseline (speedup 1.0000x reference)
.LBB0_603:
	v_sub_u32_e32 v81, 0x7f, v73
	v_cvt_f32_i32_e32 v81, v81
	s_waitcnt vmcnt(15)
	v_lshlrev_b32_e32 v75, 16, v60
	s_waitcnt vmcnt(14)
	v_lshlrev_b32_e32 v79, 16, v56
	v_and_b32_e32 v60, 0xffff0000, v60
	v_mul_f32_e32 v83, v74, v81
	v_cmp_gt_f32_e32 vcc, s75, v83
	v_and_b32_e32 v56, 0xffff0000, v56
	v_lshlrev_b32_e32 v76, 16, v61
	v_cndmask_b32_e32 v83, 0, v240, vcc
	v_fmac_f32_e32 v83, v74, v81
	v_exp_f32_e32 v81, v83
	v_cndmask_b32_e32 v84, 0, v241, vcc
	v_lshlrev_b32_e32 v80, 16, v57
	v_and_b32_e32 v61, 0xffff0000, v61
	v_ldexp_f32 v81, v81, v84
	s_waitcnt vmcnt(8)
	v_mul_f32_e32 v84, v52, v79
	v_mul_f32_e32 v52, v52, v75
	v_mul_f32_e32 v81, 0x3db504f3, v81
	v_fmac_f32_e32 v52, v48, v79
	v_fma_f32 v84, v48, v75, -v84
	v_mul_f32_e32 v48, v52, v81
	v_mul_f32_e32 v52, v53, v56
	v_mul_f32_e32 v53, v53, v60
	v_fmac_f32_e32 v53, v49, v56
	v_fma_f32 v52, v49, v60, -v52
	v_mul_f32_e32 v49, v53, v81
	v_mul_f32_e32 v53, v54, v80
	v_mul_f32_e32 v54, v54, v76
	v_and_b32_e32 v57, 0xffff0000, v57
	v_fmac_f32_e32 v54, v50, v80
	v_fma_f32 v53, v50, v76, -v53
	v_mul_f32_e32 v50, v54, v81
	v_mul_f32_e32 v54, v55, v57
	v_mul_f32_e32 v55, v55, v61
	v_lshlrev_b32_e32 v77, 16, v62
	v_lshlrev_b32_e32 v82, 16, v58
	v_fmac_f32_e32 v55, v51, v57
	v_fma_f32 v54, v51, v61, -v54
	v_mul_f32_e32 v51, v55, v81
	v_mul_f32_e32 v55, v44, v82
	v_mul_f32_e32 v44, v44, v77
	v_and_b32_e32 v62, 0xffff0000, v62
	v_and_b32_e32 v58, 0xffff0000, v58
	v_fmac_f32_e32 v44, v40, v82
	v_fma_f32 v55, v40, v77, -v55
	v_mul_f32_e32 v40, v44, v81
	v_mul_f32_e32 v44, v45, v58
	v_mul_f32_e32 v45, v45, v62
	v_lshlrev_b32_e32 v78, 16, v63
	v_lshlrev_b32_e32 v83, 16, v59
	v_fmac_f32_e32 v45, v41, v58
	v_fma_f32 v44, v41, v62, -v44
	v_mul_f32_e32 v41, v45, v81
	v_mul_f32_e32 v45, v46, v83
	v_mul_f32_e32 v46, v46, v78
	v_and_b32_e32 v63, 0xffff0000, v63
	v_and_b32_e32 v59, 0xffff0000, v59
	v_fmac_f32_e32 v46, v42, v83
	v_fma_f32 v45, v42, v78, -v45
	v_mul_f32_e32 v42, v46, v81
	v_mul_f32_e32 v46, v47, v59
	v_mul_f32_e32 v47, v47, v63
	v_fmac_f32_e32 v47, v43, v59
	v_mad_u32_u24 v56, v72, s65, 0
	v_mul_f32_e32 v84, v84, v81
	v_fma_f32 v46, v43, v63, -v46
	v_mul_f32_e32 v43, v47, v81
	v_cvt_pk_bf16_f32 v47, v84, v145
	v_and_b32_e32 v85, 3, v65
	v_lshlrev_b32_e32 v85, 4, v85
	v_lshl_add_u32 v57, v73, 1, v56
	v_xor_b32_e32 v57, v57, v85
	ds_write_b16 v57, v47
	v_cvt_pk_bf16_f32 v47, v48, v145
	v_mul_f32_e32 v52, v52, v81
	ds_write_b16 v57, v47 offset:17408
	v_cvt_pk_bf16_f32 v47, v52, v145
	ds_write_b16 v57, v47 offset:272
	v_cvt_pk_bf16_f32 v47, v49, v145
	v_mul_f32_e32 v53, v53, v81
	ds_write_b16 v57, v47 offset:17680
	v_cvt_pk_bf16_f32 v47, v53, v145
	ds_write_b16 v57, v47 offset:544
	v_cvt_pk_bf16_f32 v47, v50, v145
	v_mul_f32_e32 v54, v54, v81
	ds_write_b16 v57, v47 offset:17952
	v_cvt_pk_bf16_f32 v47, v54, v145
	ds_write_b16 v57, v47 offset:816
	v_cvt_pk_bf16_f32 v47, v51, v145
	v_mul_f32_e32 v55, v55, v81
	ds_write_b16 v57, v47 offset:18224
	v_cvt_pk_bf16_f32 v47, v55, v145
	ds_write_b16 v57, v47 offset:1088
	v_cvt_pk_bf16_f32 v40, v40, v145
	v_mul_f32_e32 v44, v44, v81
	ds_write_b16 v57, v40 offset:18496
	v_cvt_pk_bf16_f32 v40, v44, v145
	ds_write_b16 v57, v40 offset:1360
	v_cvt_pk_bf16_f32 v40, v41, v145
	v_mul_f32_e32 v45, v45, v81
	ds_write_b16 v57, v40 offset:18768
	v_cvt_pk_bf16_f32 v40, v45, v145
	v_mul_f32_e32 v46, v46, v81
	ds_write_b16 v57, v40 offset:1632
	v_cvt_pk_bf16_f32 v40, v42, v145
	ds_write_b16 v57, v40 offset:19040
	v_cvt_pk_bf16_f32 v40, v46, v145
	v_sub_u32_e32 v46, 0x7f, v70
	v_cvt_f32_i32_e32 v46, v46
	ds_write_b16 v57, v40 offset:1904
	v_cvt_pk_bf16_f32 v40, v43, v145
	ds_write_b16 v57, v40 offset:19312
	v_mul_f32_e32 v48, v74, v46
	v_cmp_gt_f32_e32 vcc, s75, v48
	v_lshlrev_b32_e32 v40, 16, v36
	v_lshlrev_b32_e32 v44, 16, v32
	v_cndmask_b32_e32 v48, 0, v240, vcc
	v_fmac_f32_e32 v48, v74, v46
	v_exp_f32_e32 v46, v48
	v_cndmask_b32_e32 v49, 0, v241, vcc
	v_and_b32_e32 v36, 0xffff0000, v36
	v_and_b32_e32 v32, 0xffff0000, v32
	v_ldexp_f32 v46, v46, v49
	s_waitcnt vmcnt(4)
	v_mul_f32_e32 v49, v28, v44
	v_mul_f32_e32 v28, v28, v40
	v_mul_f32_e32 v46, 0x3db504f3, v46
	v_fmac_f32_e32 v28, v24, v44
	v_fma_f32 v49, v24, v40, -v49
	v_mul_f32_e32 v24, v28, v46
	v_mul_f32_e32 v28, v29, v32
	v_mul_f32_e32 v29, v29, v36
	v_lshlrev_b32_e32 v41, 16, v37
	v_lshlrev_b32_e32 v45, 16, v33
	v_fmac_f32_e32 v29, v25, v32
	v_fma_f32 v28, v25, v36, -v28
	v_mul_f32_e32 v25, v29, v46
	v_mul_f32_e32 v29, v30, v45
	v_mul_f32_e32 v30, v30, v41
	v_and_b32_e32 v37, 0xffff0000, v37
	v_and_b32_e32 v33, 0xffff0000, v33
	v_fmac_f32_e32 v30, v26, v45
	v_fma_f32 v29, v26, v41, -v29
	v_mul_f32_e32 v26, v30, v46
	v_mul_f32_e32 v30, v31, v33
	v_mul_f32_e32 v31, v31, v37
	v_lshlrev_b32_e32 v42, 16, v38
	v_lshlrev_b32_e32 v47, 16, v34
	v_fmac_f32_e32 v31, v27, v33
	v_fma_f32 v30, v27, v37, -v30
	v_mul_f32_e32 v27, v31, v46
	v_mul_f32_e32 v31, v20, v47
	v_mul_f32_e32 v20, v20, v42
	v_and_b32_e32 v38, 0xffff0000, v38
	v_and_b32_e32 v34, 0xffff0000, v34
	v_fmac_f32_e32 v20, v16, v47
	v_fma_f32 v31, v16, v42, -v31
	v_mul_f32_e32 v16, v20, v46
	v_mul_f32_e32 v20, v21, v34
	v_mul_f32_e32 v21, v21, v38
	v_lshlrev_b32_e32 v43, 16, v39
	v_lshlrev_b32_e32 v48, 16, v35
	v_fmac_f32_e32 v21, v17, v34
	v_fma_f32 v20, v17, v38, -v20
	v_mul_f32_e32 v17, v21, v46
	v_mul_f32_e32 v21, v22, v48
	v_mul_f32_e32 v22, v22, v43
	v_and_b32_e32 v39, 0xffff0000, v39
	v_and_b32_e32 v35, 0xffff0000, v35
	v_fmac_f32_e32 v22, v18, v48
	v_fma_f32 v21, v18, v43, -v21
	v_mul_f32_e32 v18, v22, v46
	v_mul_f32_e32 v22, v23, v35
	v_mul_f32_e32 v23, v23, v39
	v_fmac_f32_e32 v23, v19, v35
	v_mul_f32_e32 v49, v49, v46
	v_fma_f32 v22, v19, v39, -v22
	v_mul_f32_e32 v19, v23, v46
	v_cvt_pk_bf16_f32 v23, v49, v145
	v_lshl_add_u32 v32, v70, 1, v56
	v_xor_b32_e32 v32, v32, v85
	ds_write_b16 v32, v23
	v_cvt_pk_bf16_f32 v23, v24, v145
	v_mul_f32_e32 v28, v28, v46
	ds_write_b16 v32, v23 offset:17408
	v_cvt_pk_bf16_f32 v23, v28, v145
	ds_write_b16 v32, v23 offset:272
	v_cvt_pk_bf16_f32 v23, v25, v145
	v_mul_f32_e32 v29, v29, v46
	ds_write_b16 v32, v23 offset:17680
	v_cvt_pk_bf16_f32 v23, v29, v145
	ds_write_b16 v32, v23 offset:544
	v_cvt_pk_bf16_f32 v23, v26, v145
	v_mul_f32_e32 v30, v30, v46
	ds_write_b16 v32, v23 offset:17952
	v_cvt_pk_bf16_f32 v23, v30, v145
	ds_write_b16 v32, v23 offset:816
	v_cvt_pk_bf16_f32 v23, v27, v145
	v_mul_f32_e32 v31, v31, v46
	ds_write_b16 v32, v23 offset:18224
	v_cvt_pk_bf16_f32 v23, v31, v145
	ds_write_b16 v32, v23 offset:1088
	v_cvt_pk_bf16_f32 v16, v16, v145
	v_mul_f32_e32 v20, v20, v46
	ds_write_b16 v32, v16 offset:18496
	v_cvt_pk_bf16_f32 v16, v20, v145
	ds_write_b16 v32, v16 offset:1360
	v_cvt_pk_bf16_f32 v16, v17, v145
	v_mul_f32_e32 v21, v21, v46
	ds_write_b16 v32, v16 offset:18768
	v_cvt_pk_bf16_f32 v16, v21, v145
	ds_write_b16 v32, v16 offset:1632
	v_cvt_pk_bf16_f32 v16, v18, v145
	v_mul_f32_e32 v22, v22, v46
	ds_write_b16 v32, v16 offset:19040
	v_cvt_pk_bf16_f32 v16, v22, v145
	ds_write_b16 v32, v16 offset:1904
	v_cvt_pk_bf16_f32 v16, v19, v145
	ds_write_b16 v32, v16 offset:19312
	v_mad_u32_u24 v16, v68, s65, 0
	v_lshl_add_u32 v17, v71, 1, v16
	v_xor_b32_e32 v17, v17, v85
	s_waitcnt vmcnt(3)
	ds_write_b16 v17, v12 offset:34816
	ds_write_b16_d16_hi v17, v12 offset:35088
	ds_write_b16 v17, v13 offset:35360
	ds_write_b16_d16_hi v17, v13 offset:35632
	ds_write_b16 v17, v14 offset:35904
	ds_write_b16_d16_hi v17, v14 offset:36176
	ds_write_b16 v17, v15 offset:36448
	ds_write_b16_d16_hi v17, v15 offset:36720
	v_lshl_add_u32 v12, v69, 1, v16
	v_xor_b32_e32 v12, v12, v85
	s_waitcnt vmcnt(2)
	ds_write_b16 v12, v4 offset:34816
	ds_write_b16_d16_hi v12, v4 offset:35088
	ds_write_b16 v12, v5 offset:35360
	ds_write_b16_d16_hi v12, v5 offset:35632
	ds_write_b16 v12, v6 offset:35904
	ds_write_b16_d16_hi v12, v6 offset:36176
	ds_write_b16 v12, v7 offset:36448
	ds_write_b16_d16_hi v12, v7 offset:36720
	v_lshl_add_u32 v4, v67, 1, v16
	v_xor_b32_e32 v4, v4, v85
	v_bfe_u32 v64, v65, 4, 2
	s_waitcnt vmcnt(1)
	ds_write_b16 v4, v8 offset:34816
	ds_write_b16_d16_hi v4, v8 offset:35088
	ds_write_b16 v4, v9 offset:35360
	ds_write_b16_d16_hi v4, v9 offset:35632
	ds_write_b16 v4, v10 offset:35904
	ds_write_b16_d16_hi v4, v10 offset:36176
	ds_write_b16 v4, v11 offset:36448
	ds_write_b16_d16_hi v4, v11 offset:36720
	v_lshl_add_u32 v4, v66, 1, v16
	v_xor_b32_e32 v4, v4, v85
	v_ashrrev_i32_e32 v46, 2, v65
	s_waitcnt vmcnt(0)
	ds_write_b16 v4, v0 offset:34816
	ds_write_b16_d16_hi v4, v0 offset:35088
	ds_write_b16 v4, v1 offset:35360
	ds_write_b16_d16_hi v4, v1 offset:35632
	ds_write_b16 v4, v2 offset:35904
	ds_write_b16_d16_hi v4, v2 offset:36176
	ds_write_b16 v4, v3 offset:36448
	ds_write_b16_d16_hi v4, v3 offset:36720
	v_bfi_b32 v0, -16, v46, v65
	v_lshl_add_u32 v4, v64, 4, 0
	v_mad_u64_u32 v[44:45], s[10:11], v0, s65, v[4:5]
	s_waitcnt lgkmcnt(0)
	s_barrier
	v_lshrrev_b32_e32 v86, 3, v65
	v_and_b32_e32 v86, 1, v86
	v_lshrrev_b32_e32 v87, 5, v65
	v_and_b32_e32 v87, 2, v87
	v_or_b32_e32 v87, v87, v86
	v_xor_b32_e32 v87, v87, v64
	v_sub_u32_e32 v87, v87, v64
	v_lshl_add_u32 v88, v87, 4, v44
	v_and_b32_e32 v89, 15, v65
	v_mad_u32_u24 v89, v89, s65, v4
	v_xor_b32_e32 v86, v86, v64
	v_sub_u32_e32 v87, v86, v64
	v_lshl_add_u32 v90, v87, 4, v89
	v_xor_b32_e32 v86, 2, v86
	v_sub_u32_e32 v87, v86, v64
	v_lshl_add_u32 v91, v87, 4, v89
	ds_read_b128 v[0:3], v88 offset:34816
	v_and_b32_e32 v45, 15, v65
	v_mad_u32_u24 v47, v45, s65, v4
	ds_read_b128 v[4:7], v90 offset:0
	ds_read_b128 v[8:11], v91 offset:4352
	ds_read_b128 v[12:15], v90 offset:8704
	ds_read_b128 v[16:19], v91 offset:13056
	ds_read_b128 v[20:23], v90 offset:17408
	ds_read_b128 v[24:27], v91 offset:21760
	ds_read_b128 v[28:31], v90 offset:26112
	ds_read_b128 v[32:35], v91 offset:30464
	ds_read_b128 v[36:39], v88 offset:34880
	s_waitcnt lgkmcnt(8)
	v_mfma_f32_16x16x32_bf16 v[4:7], v[0:3], v[4:7], 0
	v_readlane_b32 s0, v254, 51
	s_add_i32 s16, s16, s40
	s_add_i32 s13, s13, s61
	s_waitcnt lgkmcnt(7)
	v_mfma_f32_16x16x32_bf16 v[8:11], v[0:3], v[8:11], 0
	s_add_i32 s12, s12, s0
	s_waitcnt lgkmcnt(6)
	v_mfma_f32_16x16x32_bf16 v[12:15], v[0:3], v[12:15], 0
	s_waitcnt lgkmcnt(5)
	v_mfma_f32_16x16x32_bf16 v[16:19], v[0:3], v[16:19], 0
	s_waitcnt lgkmcnt(4)
	v_mfma_f32_16x16x32_bf16 v[20:23], v[0:3], v[20:23], 0
	s_waitcnt lgkmcnt(3)
	v_mfma_f32_16x16x32_bf16 v[24:27], v[0:3], v[24:27], 0
	s_waitcnt lgkmcnt(2)
	v_mfma_f32_16x16x32_bf16 v[28:31], v[0:3], v[28:31], 0
	s_waitcnt lgkmcnt(1)
	v_mfma_f32_16x16x32_bf16 v[0:3], v[0:3], v[32:35], 0
	ds_read_b128 v[32:35], v90 offset:64
	s_waitcnt lgkmcnt(0)
	v_mfma_f32_16x16x32_bf16 v[4:7], v[36:39], v[32:35], v[4:7]
	ds_read_b128 v[32:35], v91 offset:4416
	s_waitcnt lgkmcnt(0)
	v_mfma_f32_16x16x32_bf16 v[8:11], v[36:39], v[32:35], v[8:11]
	ds_read_b128 v[32:35], v90 offset:8768
	s_waitcnt lgkmcnt(0)
	v_mfma_f32_16x16x32_bf16 v[12:15], v[36:39], v[32:35], v[12:15]
	ds_read_b128 v[32:35], v91 offset:13120
	s_waitcnt lgkmcnt(0)
	v_mfma_f32_16x16x32_bf16 v[16:19], v[36:39], v[32:35], v[16:19]
	ds_read_b128 v[32:35], v90 offset:17472
	s_waitcnt lgkmcnt(0)
	v_mfma_f32_16x16x32_bf16 v[20:23], v[36:39], v[32:35], v[20:23]
	ds_read_b128 v[32:35], v91 offset:21824
	s_waitcnt lgkmcnt(0)
	v_mfma_f32_16x16x32_bf16 v[24:27], v[36:39], v[32:35], v[24:27]
	ds_read_b128 v[32:35], v90 offset:26176
	ds_read_b128 v[40:43], v91 offset:30528
	s_waitcnt lgkmcnt(1)
	v_mfma_f32_16x16x32_bf16 v[28:31], v[36:39], v[32:35], v[28:31]
	ds_read_b128 v[32:35], v88 offset:34944
	s_waitcnt lgkmcnt(1)
	v_mfma_f32_16x16x32_bf16 v[0:3], v[36:39], v[40:43], v[0:3]
	ds_read_b128 v[36:39], v90 offset:128
	s_waitcnt lgkmcnt(0)
	v_mfma_f32_16x16x32_bf16 v[4:7], v[32:35], v[36:39], v[4:7]
	ds_read_b128 v[36:39], v91 offset:4480
	s_waitcnt lgkmcnt(0)
	v_mfma_f32_16x16x32_bf16 v[8:11], v[32:35], v[36:39], v[8:11]
	ds_read_b128 v[36:39], v90 offset:8832
	s_waitcnt lgkmcnt(0)
	v_mfma_f32_16x16x32_bf16 v[12:15], v[32:35], v[36:39], v[12:15]
	ds_read_b128 v[36:39], v91 offset:13184
	s_waitcnt lgkmcnt(0)
	v_mfma_f32_16x16x32_bf16 v[16:19], v[32:35], v[36:39], v[16:19]
	ds_read_b128 v[36:39], v90 offset:17536
	s_waitcnt lgkmcnt(0)
	v_mfma_f32_16x16x32_bf16 v[20:23], v[32:35], v[36:39], v[20:23]
	ds_read_b128 v[36:39], v91 offset:21888
	s_waitcnt lgkmcnt(0)
	v_mfma_f32_16x16x32_bf16 v[24:27], v[32:35], v[36:39], v[24:27]
	ds_read_b128 v[36:39], v90 offset:26240
	ds_read_b128 v[40:43], v91 offset:30592
	s_waitcnt lgkmcnt(1)
	v_mfma_f32_16x16x32_bf16 v[28:31], v[32:35], v[36:39], v[28:31]
	ds_read_b128 v[36:39], v88 offset:35008
	s_waitcnt lgkmcnt(1)
	v_mfma_f32_16x16x32_bf16 v[0:3], v[32:35], v[40:43], v[0:3]
	ds_read_b128 v[32:35], v90 offset:192
	v_and_b32_e32 v40, -16, v46
	s_waitcnt lgkmcnt(0)
	v_mfma_f32_16x16x32_bf16 v[4:7], v[36:39], v[32:35], v[4:7]
	ds_read_b128 v[32:35], v91 offset:4544
	s_waitcnt lgkmcnt(0)
	v_mfma_f32_16x16x32_bf16 v[8:11], v[36:39], v[32:35], v[8:11]
	ds_read_b128 v[32:35], v90 offset:8896
	s_waitcnt lgkmcnt(0)
	v_mfma_f32_16x16x32_bf16 v[12:15], v[36:39], v[32:35], v[12:15]
	ds_read_b128 v[32:35], v91 offset:13248
	s_waitcnt lgkmcnt(0)
	v_mfma_f32_16x16x32_bf16 v[16:19], v[36:39], v[32:35], v[16:19]
	ds_read_b128 v[32:35], v90 offset:17600
	s_waitcnt lgkmcnt(0)
	v_mfma_f32_16x16x32_bf16 v[20:23], v[36:39], v[32:35], v[20:23]
	ds_read_b128 v[32:35], v91 offset:21952
	s_waitcnt lgkmcnt(0)
	v_mfma_f32_16x16x32_bf16 v[24:27], v[36:39], v[32:35], v[24:27]
	ds_read_b128 v[32:35], v90 offset:26304
	s_waitcnt lgkmcnt(0)
	v_mfma_f32_16x16x32_bf16 v[28:31], v[36:39], v[32:35], v[28:31]
	ds_read_b128 v[32:35], v91 offset:30656
	s_waitcnt lgkmcnt(0)
	v_mfma_f32_16x16x32_bf16 v[0:3], v[36:39], v[32:35], v[0:3]
	v_lshlrev_b32_e32 v32, 7, v40
	v_lshl_or_b32 v36, v64, 9, v32
	v_or_b32_e32 v32, v36, v45
	v_ashrrev_i32_e32 v33, 31, v32
	v_lshl_add_u64 v[34:35], v[32:33], 2, s[8:9]
	v_ashrrev_i32_e32 v33, 31, v36
	v_lshl_add_u64 v[32:33], v[32:33], 2, s[8:9]
	s_add_u32 s8, s8, s78
	s_addc_u32 s9, s9, s79
	s_cmpk_gt_i32 s16, 0x1ff
	global_store_dword v[34:35], v4, off offset:-1984
	global_store_dword v[32:33], v5, off offset:-1472
	global_store_dword v[32:33], v6, off offset:-960
	global_store_dword v[32:33], v7, off offset:-448
	global_store_dword v[32:33], v8, off offset:-1920
	global_store_dword v[32:33], v9, off offset:-1408
	global_store_dword v[32:33], v10, off offset:-896
	global_store_dword v[32:33], v11, off offset:-384
	global_store_dword v[32:33], v12, off offset:-1856
	global_store_dword v[32:33], v13, off offset:-1344
	global_store_dword v[32:33], v14, off offset:-832
	global_store_dword v[32:33], v15, off offset:-320
	global_store_dword v[32:33], v16, off offset:-1792
	global_store_dword v[32:33], v17, off offset:-1280
	global_store_dword v[32:33], v18, off offset:-768
	global_store_dword v[32:33], v19, off offset:-256
	global_store_dword v[32:33], v20, off offset:-1728
	global_store_dword v[32:33], v21, off offset:-1216
	global_store_dword v[32:33], v22, off offset:-704
	global_store_dword v[32:33], v23, off offset:-192
	global_store_dword v[32:33], v24, off offset:-1664
	global_store_dword v[32:33], v25, off offset:-1152
	global_store_dword v[32:33], v26, off offset:-640
	global_store_dword v[32:33], v27, off offset:-128
	global_store_dword v[32:33], v28, off offset:-1600
	global_store_dword v[32:33], v29, off offset:-1088
	global_store_dword v[32:33], v30, off offset:-576
	global_store_dword v[32:33], v31, off offset:-64
	global_store_dword v[32:33], v0, off offset:-1536
	global_store_dword v[32:33], v1, off offset:-1024
	global_store_dword v[32:33], v2, off offset:-512
	global_store_dword v[32:33], v3, off
	s_barrier
	s_cbranch_scc1 .LBB0_608
